# residual-GEMM tail tiles placed on four XCDs (two N tiles each)
# baseline (speedup 1.0000x reference)
;     ...
;   for (int it = 0;; it++) {
;     int tile;
;     if (nb == 512) tile = ((it * 8 + (bid & 7)) << 6) + (bid >> 3); else tile = it * nb + bid;
;     tile += tbeg;
;     if (tile >= MTX * ntn || tile >= tend) break;
;     int mt, nt;
;     if (tile < nfull) { const int b_ = tile / band, w_ = tile - b_ * band; nt = w_ >> 3; mt = b_ * 8 + (w_ & 7); }
;     else { const int w_ = tile - nfull; nt = w_ / MREM; mt = (MTX / 8) * 8 + (w_ - nt * MREM); }
;     const int m0 = mt * BM, n0 = nt * 128;
; __device__ __forceinline__ void run_phase(const Params& p, int ph, char* smraw, int bid, int nb) {
;     ...
;         gemm_phase<EPI_RESID, false>(A, lda, W, K, 8, e, smb, bid, nb, 2048, 2080);
.LBB0_2592:
	v_mov_b32_e32 v8, v2
	v_readlane_b32 s4, v244, 27
	s_lshr_b32 s13, s4, 3
	s_and_b32 s4, s4, 7
	s_lshl_b32 s14, s4, 1
	s_lshr_b32 s5, s13, 2
	s_add_i32 s14, s14, s5
	s_lshl_b32 s14, s14, 2
	s_and_b32 s5, s13, 3
	s_or_b32 s14, s14, s5
	s_cmp_lt_u32 s4, 4
	s_cselect_b32 s14, s14, 32
	s_cmp_lt_u32 s13, 8
	s_cselect_b32 s13, s14, 32
	s_mov_b32 s14, s13
	s_cmp_gt_i32 s13, 31
	s_cbranch_scc1 .LBB0_2612
	v_lshrrev_b32_e32 v13, 4, v8
	v_xor_b32_e32 v14, v13, v8
	v_ashrrev_i32_e32 v10, 6, v8
	v_ashrrev_i32_e32 v11, 7, v8
	v_ashrrev_i32_e32 v94, 3, v8
	v_and_b32_e32 v15, 15, v8
	v_bfe_u32 v16, v8, 4, 2
	s_waitcnt lgkmcnt(1)
	v_bfe_u32 v17, v8, 1, 3
	v_lshlrev_b32_e32 v8, 4, v14
	v_readlane_b32 s4, v244, 23
	v_and_b32_e32 v8, 0x70, v8
	v_readlane_b32 s5, v244, 24
	s_waitcnt lgkmcnt(0)
	v_and_b32_e32 v12, 1, v10
	s_and_b32 s15, s14, 3
	v_lshl_add_u64 v[74:75], s[4:5], 0, v[8:9]
	v_readlane_b32 s4, v244, 21
	v_readlane_b32 s5, v244, 22
	v_lshlrev_b32_e32 v95, 10, v10
	v_lshl_or_b32 v96, v11, 6, v15
	v_lshl_add_u64 v[76:77], s[4:5], 0, v[8:9]
	v_lshlrev_b32_e32 v8, 2, v16
	v_readlane_b32 s4, v244, 15
	v_lshl_or_b32 v97, v12, 6, v8
	v_bitop3_b32 v8, v13, v17, 3 bitop3:0x6c
	v_readlane_b32 s5, v244, 16
	v_lshlrev_b32_e32 v98, 3, v8
	v_bitop3_b32 v8, v16, v17, 4 bitop3:0x36
	s_mov_b32 s5, s4
	v_lshlrev_b32_e32 v99, 13, v11
	v_lshlrev_b32_e32 v100, 7, v15
	v_lshlrev_b32_e32 v101, 13, v12
	v_lshlrev_b32_e32 v102, 3, v8
	s_bitset1_b32 s15, 8
	s_and_b32 s14, s14, 7
	v_writelane_b32 v244, s4, 15
	s_mov_b32 s16, 0
	s_mov_b32 s2, s13
	v_writelane_b32 v244, s5, 16
	s_branch .LBB0_2595
